# decode-row epilogues of w_o and down: residual and gain loads issued before the (now combined) exchange polls
# baseline (speedup 1.0000x reference)
.LBB0_876:
	s_or_b64 exec, exec, s[24:25]
	v_lshl_or_b32 v236, s16, 5, v0
	v_lshl_or_b32 v238, s40, 4, v1
	v_ashrrev_i32_e32 v237, 31, v236
	v_lshlrev_b32_e32 v238, 12, v238
	v_mov_b32_e32 v239, v9
	v_readlane_b32 s42, v252, 16
	v_readlane_b32 s43, v252, 17
	v_readlane_b32 s50, v252, 24
	v_readlane_b32 s51, v252, 25
	v_lshlrev_b64 v[240:241], 2, v[236:237]
	v_lshl_add_u64 v[238:239], s[42:43], 0, v[238:239]
	v_lshl_add_u64 v[244:245], s[50:51], 0, v[240:241]
	v_lshl_add_u64 v[242:243], v[238:239], 0, v[240:241]
	global_load_dwordx4 v[218:221], v[242:243], off
	global_load_dwordx4 v[222:225], v[244:245], off
	global_load_dwordx4 v[226:229], v[244:245], off offset:16
	global_load_dwordx4 v[230:233], v[242:243], off offset:16
	v_lshlrev_b32_e32 v8, 3, v12
	v_lshl_add_u64 v[28:29], s[0:1], 0, v[8:9]
	v_lshlrev_b32_e32 v18, 3, v0
	v_mov_b32_e32 v19, v9
	s_lshl_b32 s17, s40, 9
	v_lshl_add_u64 v[28:29], v[28:29], 0, v[18:19]
	s_waitcnt lgkmcnt(0)
	s_mov_b32 s24, 0

.Lxch8_wo1_ready:
	v_mov_b32_e32 v14, v200
	v_mov_b32_e32 v17, v202
	v_mov_b32_e32 v19, v204
	v_mov_b32_e32 v39, v206
	v_mov_b32_e32 v40, v208
	v_mov_b32_e32 v41, v210
	v_mov_b32_e32 v42, v212
	v_mov_b32_e32 v43, v214
	v_lshl_or_b32 v30, s16, 5, v0
	v_lshl_or_b32 v28, s40, 4, v1
	v_readlane_b32 s40, v252, 14
	v_ashrrev_i32_e32 v31, 31, v30
	v_lshlrev_b32_e32 v44, 12, v28
	v_mov_b32_e32 v45, v9
	v_readlane_b32 s42, v252, 16
	v_readlane_b32 s43, v252, 17
	v_readlane_b32 s50, v252, 24
	v_readlane_b32 s51, v252, 25
	v_lshl_add_u64 v[44:45], s[42:43], 0, v[44:45]
	v_lshlrev_b64 v[46:47], 2, v[30:31]
	v_lshl_add_u64 v[56:57], v[44:45], 0, v[46:47]
	v_lshl_add_u64 v[52:53], s[50:51], 0, v[46:47]
	s_nop 0
	s_nop 0
	v_add_f32_e32 v14, 0, v14
	v_add_f32_e32 v14, v14, v17
	v_add_f32_e32 v14, v14, v19
	v_add_f32_e32 v14, v14, v39
	v_add_f32_e32 v14, v14, v40
	v_add_f32_e32 v14, v14, v41
	v_add_f32_e32 v14, v14, v42
	v_add_f32_e32 v14, v14, v43
	ds_bpermute_b32 v17, v37, v14
	v_readlane_b32 s41, v252, 15
	v_readlane_b32 s44, v252, 18
	v_readlane_b32 s45, v252, 19
	v_readlane_b32 s46, v252, 20
	s_waitcnt lgkmcnt(0)
	v_add_f32_e32 v14, v14, v17
	ds_bpermute_b32 v17, v38, v14
	v_readlane_b32 s47, v252, 21
	v_readlane_b32 s40, v252, 0
	v_readlane_b32 s44, v252, 4
	v_readlane_b32 s45, v252, 5
	s_waitcnt lgkmcnt(0)
	v_add_f32_e32 v14, v14, v17
	v_fmamk_f32 v14, v14, 0x3a800000, v35
	v_mul_f32_e32 v17, 0x4f800000, v14
	v_cmp_gt_f32_e32 vcc, s35, v14
	v_readlane_b32 s46, v252, 6
	v_readlane_b32 s47, v252, 7
	v_cndmask_b32_e32 v14, v14, v17, vcc
	v_sqrt_f32_e32 v17, v14
	s_mov_b64 s[24:25], s[44:45]
	v_mov_b32_e32 v41, v9
	v_lshlrev_b32_e32 v40, 11, v28
	v_add_u32_e32 v19, -1, v17
	v_add_u32_e32 v29, 1, v17
	v_fma_f32 v39, -v19, v17, v14
	v_fma_f32 v42, -v29, v17, v14
	v_cmp_ge_f32_e64 s[0:1], 0, v39
	s_mov_b64 s[26:27], s[46:47]
	v_lshl_add_u64 v[40:41], s[26:27], 0, v[40:41]
	v_cndmask_b32_e64 v17, v17, v19, s[0:1]
	v_cmp_lt_f32_e64 s[0:1], 0, v42
	v_lshl_add_u64 v[30:31], v[30:31], 1, v[40:41]
	v_readlane_b32 s48, v252, 22
	v_cndmask_b32_e64 v17, v17, v29, s[0:1]
	v_mul_f32_e32 v19, 0x37800000, v17
	v_cndmask_b32_e32 v17, v17, v19, vcc
	v_cmp_class_f32_e32 vcc, v14, v36
	v_readlane_b32 s49, v252, 23
	v_readlane_b32 s52, v252, 26
	v_cndmask_b32_e32 v14, v17, v14, vcc
	v_div_scale_f32 v17, s[0:1], v14, v14, 1.0
	v_rcp_f32_e32 v19, v17
	v_div_scale_f32 v29, vcc, 1.0, v14, 1.0
	s_lshl_b32 s0, s17, 3
	v_fma_f32 v39, -v17, v19, 1.0
	v_fmac_f32_e32 v19, v39, v19
	v_mul_f32_e32 v39, v29, v19
	v_fma_f32 v40, -v17, v39, v29
	v_fmac_f32_e32 v39, v40, v19
	v_fma_f32 v17, -v17, v39, v29
	v_div_fmas_f32 v17, v17, v19, v39
	v_div_fixup_f32 v14, v17, v14, 1.0
	v_pk_mul_f32 v[24:25], v[24:25], v[14:15] op_sel_hi:[1,0]
	v_pk_mul_f32 v[20:21], v[20:21], v[14:15] op_sel_hi:[1,0]
	v_pk_mul_f32 v[26:27], v[26:27], v[14:15] op_sel_hi:[1,0]
	v_pk_mul_f32 v[22:23], v[22:23], v[14:15] op_sel_hi:[1,0]
	s_add_u32 s0, s26, s0
	s_addc_u32 s1, s27, 0
	s_add_u32 s0, s0, 0xe4a8000
	s_addc_u32 s1, s1, 0
	v_readlane_b32 s53, v252, 27
	v_readlane_b32 s54, v252, 28
	v_readlane_b32 s55, v252, 29
	v_readlane_b32 s41, v252, 1
	v_readlane_b32 s42, v252, 2
	v_readlane_b32 s43, v252, 3
	s_waitcnt vmcnt(0)
	v_pk_fma_f32 v[40:41], v[224:225], v[20:21], v[220:221]
	v_pk_fma_f32 v[24:25], v[222:223], v[24:25], v[218:219]
	s_waitcnt vmcnt(0)
	v_pk_fma_f32 v[42:43], v[228:229], v[22:23], v[232:233]
	v_pk_fma_f32 v[26:27], v[226:227], v[26:27], v[230:231]
	v_cvt_pk_bf16_f32 v20, v24, v25
	v_mul_f32_e32 v14, v25, v25
	v_mul_f32_e32 v17, v41, v41
	v_mul_f32_e32 v19, v27, v27
	v_mul_f32_e32 v25, v43, v43
	v_fmac_f32_e32 v14, v24, v24
	v_fmac_f32_e32 v17, v40, v40
	v_fmac_f32_e32 v19, v26, v26
	v_fmac_f32_e32 v25, v42, v42
	v_add_f32_e32 v14, v14, v17
	v_add_f32_e32 v17, v19, v25
	v_add_f32_e32 v14, v14, v17
	ds_bpermute_b32 v17, v37, v14
	v_add_co_u32_e32 v24, vcc, s36, v30
	v_cvt_pk_bf16_f32 v21, v40, v41
	v_cvt_pk_bf16_f32 v22, v26, v27
	s_waitcnt lgkmcnt(0)
	v_add_f32_e32 v14, v14, v17
	ds_bpermute_b32 v17, v38, v14
	v_addc_co_u32_e32 v25, vcc, 0, v31, vcc
	v_cvt_pk_bf16_f32 v23, v42, v43
	global_store_dwordx4 v[24:25], v[20:23], off sc0 sc1
	s_and_saveexec_b64 s[24:25], s[6:7]
	s_cbranch_execz .LBB0_942
	s_waitcnt lgkmcnt(0)
	v_add_f32_e32 v14, v14, v17
	v_mov_b32_e32 v17, v9
	v_lshl_add_u64 v[16:17], s[0:1], 0, v[16:17]
	s_ashr_i32 s17, s16, 31
	v_lshl_add_u64 v[16:17], s[16:17], 3, v[16:17]
	global_store_dwordx2 v[16:17], v[14:15], off sc1
